# P0: x rows to bf16 with whole rows in flight one row ahead (was one wait per 1 KiB quarter row)
# speedup vs baseline: 1.0052x; 1.0007x over previous
; template <int W>
; __device__ __forceinline__ void cvt_rows(const float* srcP, const float* srcS, bf16* dst, int gw, int NGW, int lane) {
;     for (int m = gw; m < MP; m += NGW) {
;         const float* src = m < MPROMPT ? srcP + (size_t)m * W : srcS + (size_t)(m - MPROMPT) * W;
; #pragma unroll
;         for (int j = 0; j < W / 256; ++j) { f32x4 v = (f32x4){0.f, 0.f, 0.f, 0.f}; if (m < MREAL) v = __builtin_nontemporal_load((const f32x4*)src + 64 * j + lane);
;             u32x2 w; w.x = cvt_pk_bf16(v[0], v[1]); w.y = cvt_pk_bf16(v[2], v[3]); *((u32x2*)(dst + (size_t)m * W) + 64 * j + lane) = w; }
.LBB0_37:
	s_or_b64 exec, exec, s[8:9]
	s_mov_b64 s[0:1], s[56:57]
	s_waitcnt lgkmcnt(0)
	s_mov_b64 s[6:7], s[56:57]
	s_mov_b64 s[10:11], s[56:57]
	s_cmpk_gt_i32 s94, 0x40ff
	s_cbranch_scc1 .LBB0_51
	s_load_dwordx2 s[12:13], s[10:11], 0x108
	s_load_dwordx2 s[14:15], s[0:1], 0x0
	s_load_dwordx2 s[8:9], s[6:7], 0x8
	s_mov_b32 s93, s95
	v_lshlrev_b32_e32 v8, 4, v152
	v_lshlrev_b32_e32 v9, 3, v152
	s_waitcnt lgkmcnt(0)
	s_lshl_b32 s0, s94, 12
	s_add_u32 s10, s14, s0
	s_addc_u32 s11, s15, 0
	s_lshl_b32 s0, s94, 11
	s_add_u32 s18, s12, 0x2b30000
	s_addc_u32 s19, s13, 0
	s_add_u32 s18, s18, s0
	s_addc_u32 s19, s19, 0
	global_load_dwordx4 v[16:19], v8, s[10:11] nt
	global_load_dwordx4 v[20:23], v8, s[10:11] offset:1024 nt
	global_load_dwordx4 v[24:27], v8, s[10:11] offset:2048 nt
	global_load_dwordx4 v[28:31], v8, s[10:11] offset:3072 nt
	s_add_u32 s10, s10, 0x800000
	s_addc_u32 s11, s11, 0
	global_load_dwordx4 v[32:35], v8, s[10:11] nt
	global_load_dwordx4 v[36:39], v8, s[10:11] offset:1024 nt
	global_load_dwordx4 v[40:43], v8, s[10:11] offset:2048 nt
	global_load_dwordx4 v[44:47], v8, s[10:11] offset:3072 nt
	s_waitcnt vmcnt(4)
	v_cvt_pk_bf16_f32 v0, v16, v17
	v_cvt_pk_bf16_f32 v1, v18, v19
	v_cvt_pk_bf16_f32 v2, v20, v21
	v_cvt_pk_bf16_f32 v3, v22, v23
	v_cvt_pk_bf16_f32 v4, v24, v25
	v_cvt_pk_bf16_f32 v5, v26, v27
	v_cvt_pk_bf16_f32 v6, v28, v29
	v_cvt_pk_bf16_f32 v7, v30, v31
	global_store_dwordx2 v9, v[0:1], s[18:19]
	global_store_dwordx2 v9, v[2:3], s[18:19] offset:512
	global_store_dwordx2 v9, v[4:5], s[18:19] offset:1024
	global_store_dwordx2 v9, v[6:7], s[18:19] offset:1536
	s_add_u32 s18, s18, 0x400000
	s_addc_u32 s19, s19, 0
	s_add_u32 s10, s10, 0x800000
	s_addc_u32 s11, s11, 0
	global_load_dwordx4 v[16:19], v8, s[10:11] nt
	global_load_dwordx4 v[20:23], v8, s[10:11] offset:1024 nt
	global_load_dwordx4 v[24:27], v8, s[10:11] offset:2048 nt
	global_load_dwordx4 v[28:31], v8, s[10:11] offset:3072 nt
	s_waitcnt vmcnt(4)
	v_cvt_pk_bf16_f32 v0, v32, v33
	v_cvt_pk_bf16_f32 v1, v34, v35
	v_cvt_pk_bf16_f32 v2, v36, v37
	v_cvt_pk_bf16_f32 v3, v38, v39
	v_cvt_pk_bf16_f32 v4, v40, v41
	v_cvt_pk_bf16_f32 v5, v42, v43
	v_cvt_pk_bf16_f32 v6, v44, v45
	v_cvt_pk_bf16_f32 v7, v46, v47
	global_store_dwordx2 v9, v[0:1], s[18:19]
	global_store_dwordx2 v9, v[2:3], s[18:19] offset:512
	global_store_dwordx2 v9, v[4:5], s[18:19] offset:1024
	global_store_dwordx2 v9, v[6:7], s[18:19] offset:1536
	s_add_u32 s18, s18, 0x400000
	s_addc_u32 s19, s19, 0
	s_add_u32 s10, s10, 0x800000
	s_addc_u32 s11, s11, 0
	global_load_dwordx4 v[32:35], v8, s[10:11] nt
	global_load_dwordx4 v[36:39], v8, s[10:11] offset:1024 nt
	global_load_dwordx4 v[40:43], v8, s[10:11] offset:2048 nt
	global_load_dwordx4 v[44:47], v8, s[10:11] offset:3072 nt
	s_waitcnt vmcnt(4)
	v_cvt_pk_bf16_f32 v0, v16, v17
	v_cvt_pk_bf16_f32 v1, v18, v19
	v_cvt_pk_bf16_f32 v2, v20, v21
	v_cvt_pk_bf16_f32 v3, v22, v23
	v_cvt_pk_bf16_f32 v4, v24, v25
	v_cvt_pk_bf16_f32 v5, v26, v27
	v_cvt_pk_bf16_f32 v6, v28, v29
	v_cvt_pk_bf16_f32 v7, v30, v31
	global_store_dwordx2 v9, v[0:1], s[18:19]
	global_store_dwordx2 v9, v[2:3], s[18:19] offset:512
	global_store_dwordx2 v9, v[4:5], s[18:19] offset:1024
	global_store_dwordx2 v9, v[6:7], s[18:19] offset:1536
	s_add_u32 s18, s18, 0x400000
	s_addc_u32 s19, s19, 0
	s_add_u32 s10, s10, 0x800000
	s_addc_u32 s11, s11, 0
	global_load_dwordx4 v[16:19], v8, s[10:11] nt
	global_load_dwordx4 v[20:23], v8, s[10:11] offset:1024 nt
	global_load_dwordx4 v[24:27], v8, s[10:11] offset:2048 nt
	global_load_dwordx4 v[28:31], v8, s[10:11] offset:3072 nt
	s_waitcnt vmcnt(4)
	v_cvt_pk_bf16_f32 v0, v32, v33
	v_cvt_pk_bf16_f32 v1, v34, v35
	v_cvt_pk_bf16_f32 v2, v36, v37
	v_cvt_pk_bf16_f32 v3, v38, v39
	v_cvt_pk_bf16_f32 v4, v40, v41
	v_cvt_pk_bf16_f32 v5, v42, v43
	v_cvt_pk_bf16_f32 v6, v44, v45
	v_cvt_pk_bf16_f32 v7, v46, v47
	global_store_dwordx2 v9, v[0:1], s[18:19]
	global_store_dwordx2 v9, v[2:3], s[18:19] offset:512
	global_store_dwordx2 v9, v[4:5], s[18:19] offset:1024
	global_store_dwordx2 v9, v[6:7], s[18:19] offset:1536
	s_add_u32 s18, s18, 0x400000
	s_addc_u32 s19, s19, 0
	s_add_u32 s10, s10, 0x800000
	s_addc_u32 s11, s11, 0
	global_load_dwordx4 v[32:35], v8, s[10:11] nt
	global_load_dwordx4 v[36:39], v8, s[10:11] offset:1024 nt
	global_load_dwordx4 v[40:43], v8, s[10:11] offset:2048 nt
	global_load_dwordx4 v[44:47], v8, s[10:11] offset:3072 nt
	s_waitcnt vmcnt(4)
; template <int W>
; __device__ __forceinline__ void cvt_rows(const float* srcP, const float* srcS, bf16* dst, int gw, int NGW, int lane) {
;     for (int m = gw; m < MP; m += NGW) {
;         const float* src = m < MPROMPT ? srcP + (size_t)m * W : srcS + (size_t)(m - MPROMPT) * W;
; #pragma unroll
;         for (int j = 0; j < W / 256; ++j) { f32x4 v = (f32x4){0.f, 0.f, 0.f, 0.f}; if (m < MREAL) v = __builtin_nontemporal_load((const f32x4*)src + 64 * j + lane);
;             u32x2 w; w.x = cvt_pk_bf16(v[0], v[1]); w.y = cvt_pk_bf16(v[2], v[3]); *((u32x2*)(dst + (size_t)m * W) + 64 * j + lane) = w; }
;     }
	v_cvt_pk_bf16_f32 v0, v16, v17
	v_cvt_pk_bf16_f32 v1, v18, v19
	v_cvt_pk_bf16_f32 v2, v20, v21
	v_cvt_pk_bf16_f32 v3, v22, v23
	v_cvt_pk_bf16_f32 v4, v24, v25
	v_cvt_pk_bf16_f32 v5, v26, v27
	v_cvt_pk_bf16_f32 v6, v28, v29
	v_cvt_pk_bf16_f32 v7, v30, v31
	global_store_dwordx2 v9, v[0:1], s[18:19]
	global_store_dwordx2 v9, v[2:3], s[18:19] offset:512
	global_store_dwordx2 v9, v[4:5], s[18:19] offset:1024
	global_store_dwordx2 v9, v[6:7], s[18:19] offset:1536
	s_add_u32 s18, s18, 0x400000
	s_addc_u32 s19, s19, 0
	s_add_u32 s10, s10, 0x800000
	s_addc_u32 s11, s11, 0
	global_load_dwordx4 v[16:19], v8, s[10:11] nt
	global_load_dwordx4 v[20:23], v8, s[10:11] offset:1024 nt
	global_load_dwordx4 v[24:27], v8, s[10:11] offset:2048 nt
	global_load_dwordx4 v[28:31], v8, s[10:11] offset:3072 nt
	s_waitcnt vmcnt(4)
	v_cvt_pk_bf16_f32 v0, v32, v33
	v_cvt_pk_bf16_f32 v1, v34, v35
	v_cvt_pk_bf16_f32 v2, v36, v37
	v_cvt_pk_bf16_f32 v3, v38, v39
	v_cvt_pk_bf16_f32 v4, v40, v41
	v_cvt_pk_bf16_f32 v5, v42, v43
	v_cvt_pk_bf16_f32 v6, v44, v45
	v_cvt_pk_bf16_f32 v7, v46, v47
	global_store_dwordx2 v9, v[0:1], s[18:19]
	global_store_dwordx2 v9, v[2:3], s[18:19] offset:512
	global_store_dwordx2 v9, v[4:5], s[18:19] offset:1024
	global_store_dwordx2 v9, v[6:7], s[18:19] offset:1536
	s_add_u32 s18, s18, 0x400000
	s_addc_u32 s19, s19, 0
	s_add_u32 s10, s10, 0x800000
	s_addc_u32 s11, s11, 0
	global_load_dwordx4 v[32:35], v8, s[10:11] nt
	global_load_dwordx4 v[36:39], v8, s[10:11] offset:1024 nt
	global_load_dwordx4 v[40:43], v8, s[10:11] offset:2048 nt
	global_load_dwordx4 v[44:47], v8, s[10:11] offset:3072 nt
	s_waitcnt vmcnt(4)
	v_cvt_pk_bf16_f32 v0, v16, v17
	v_cvt_pk_bf16_f32 v1, v18, v19
	v_cvt_pk_bf16_f32 v2, v20, v21
	v_cvt_pk_bf16_f32 v3, v22, v23
	v_cvt_pk_bf16_f32 v4, v24, v25
	v_cvt_pk_bf16_f32 v5, v26, v27
	v_cvt_pk_bf16_f32 v6, v28, v29
	v_cvt_pk_bf16_f32 v7, v30, v31
	global_store_dwordx2 v9, v[0:1], s[18:19]
	global_store_dwordx2 v9, v[2:3], s[18:19] offset:512
	global_store_dwordx2 v9, v[4:5], s[18:19] offset:1024
	global_store_dwordx2 v9, v[6:7], s[18:19] offset:1536
	s_add_u32 s18, s18, 0x400000
	s_addc_u32 s19, s19, 0
	s_waitcnt vmcnt(0)
	v_cvt_pk_bf16_f32 v0, v32, v33
	v_cvt_pk_bf16_f32 v1, v34, v35
	v_cvt_pk_bf16_f32 v2, v36, v37
	v_cvt_pk_bf16_f32 v3, v38, v39
	v_cvt_pk_bf16_f32 v4, v40, v41
	v_cvt_pk_bf16_f32 v5, v42, v43
	v_cvt_pk_bf16_f32 v6, v44, v45
	v_cvt_pk_bf16_f32 v7, v46, v47
	global_store_dwordx2 v9, v[0:1], s[18:19]
	global_store_dwordx2 v9, v[2:3], s[18:19] offset:512
	global_store_dwordx2 v9, v[4:5], s[18:19] offset:1024
	global_store_dwordx2 v9, v[6:7], s[18:19] offset:1536
	s_add_u32 s18, s18, 0x400000
	s_addc_u32 s19, s19, 0
	s_cmpk_gt_u32 s94, 0xff
	s_cbranch_scc1 .LBB0_50
	s_cmpk_gt_u32 s94, 0x7f
	s_cbranch_scc1 .Lcvt_zero
	s_lshl_b32 s0, s94, 12
	s_add_u32 s10, s8, s0
	s_addc_u32 s11, s9, 0
	global_load_dwordx4 v[16:19], v8, s[10:11] nt
	global_load_dwordx4 v[20:23], v8, s[10:11] offset:1024 nt
	global_load_dwordx4 v[24:27], v8, s[10:11] offset:2048 nt
	global_load_dwordx4 v[28:31], v8, s[10:11] offset:3072 nt
	s_waitcnt vmcnt(0)
	v_cvt_pk_bf16_f32 v0, v16, v17
	v_cvt_pk_bf16_f32 v1, v18, v19
	v_cvt_pk_bf16_f32 v2, v20, v21
	v_cvt_pk_bf16_f32 v3, v22, v23
	v_cvt_pk_bf16_f32 v4, v24, v25
	v_cvt_pk_bf16_f32 v5, v26, v27
	v_cvt_pk_bf16_f32 v6, v28, v29
	v_cvt_pk_bf16_f32 v7, v30, v31
	global_store_dwordx2 v9, v[0:1], s[18:19]
	global_store_dwordx2 v9, v[2:3], s[18:19] offset:512
	global_store_dwordx2 v9, v[4:5], s[18:19] offset:1024
	global_store_dwordx2 v9, v[6:7], s[18:19] offset:1536
	s_branch .LBB0_50
.Lcvt_zero:
	v_mov_b32_e32 v0, 0
	v_mov_b32_e32 v1, 0
	global_store_dwordx2 v9, v[0:1], s[18:19]
	global_store_dwordx2 v9, v[0:1], s[18:19] offset:512
	global_store_dwordx2 v9, v[0:1], s[18:19] offset:1024
	global_store_dwordx2 v9, v[0:1], s[18:19] offset:1536
